# SWA loop: skip trailing fully-masked wave-tiles (drone path), on top of MLA changes
# speedup vs baseline: 1.0113x; 1.0062x over previous
; template <int DQ, int DK1, int DV, int MODE> ...
;     ...
;     for (int kt = kt0; kt < kt1; ++kt) {
;         const int cur = (kt - kt0) & 1; const bool more1 = kt + 1 < kt1, more2 = kt + 2 < kt1;
;         if (more2) dma_k(kt + 2, cur);
;     ...
;         asm volatile("s_waitcnt vmcnt(0)" ::: "memory");
;         __syncthreads();
;         p0 = n0; p1 = n1;
;     }
.Lswa_drone:
	s_add_i32 s40, s40, 64
	s_add_i32 s29, s29, 1
	v_lshl_add_u64 v[102:103], v[102:103], 0, s[74:75]
	v_lshl_add_u64 v[104:105], v[104:105], 0, s[74:75]
	v_lshl_add_u64 v[106:107], v[106:107], 0, s[74:75]
	v_lshl_add_u64 v[108:109], v[108:109], 0, s[74:75]
	s_waitcnt vmcnt(0)
	s_barrier
	s_cmp_lt_u32 s41, s18
	s_cbranch_scc1 .LBB0_307
	s_branch .Lswa_epi

; template <int DQ, int DK1, int DV, int MODE> ...
;     ...
;             const bool diag = (64 * kt + 63 > q0w) || (MODE == 2 && 64 * kt <= q0w + 31 - 128);
;             if (diag) {
; #pragma unroll
;                 for (int i = 0; i < 16; ++i) { const int key = 64 * kt + (i & 3) + 8 * (i >> 2) + 4 * hi;
;                     bool ok0 = key <= qpos, ok1 = key + 32 <= qpos;
;                     if (MODE == 2) { ok0 = ok0 && key > qpos - 128; ok1 = ok1 && key + 32 > qpos - 128; }
;                     if (!ok0) p0[i] = -INFINITY; if (!ok1) p1[i] = -INFINITY; }
.LBB0_317:
	s_add_i32 s10, s21, 0x9f
	s_cmp_gt_i32 s40, s10
	s_cbranch_scc1 .Lswa_drone
	s_add_i32 s12, s40, 0xffffff80
	s_add_i32 s10, s40, 0xffffffbf
	s_cmp_gt_i32 s10, s21
	s_cselect_b64 s[10:11], -1, 0
	s_cmp_le_i32 s12, s39
	s_cselect_b64 s[12:13], -1, 0
	s_or_b64 s[10:11], s[10:11], s[12:13]
	s_andn2_b64 vcc, exec, s[10:11]
	s_cbranch_vccnz .LBB0_319
	v_add_u32_e32 v81, s40, v111
	v_add_u32_e32 v67, 0xffffff80, v81
	v_cmp_le_i32_e32 vcc, v67, v100
	v_add_u32_e32 v66, 0xffffffa0, v81
	v_cmp_gt_i32_e64 s[12:13], v67, v136
	v_cmp_le_i32_e64 s[10:11], v66, v100
	s_and_b64 vcc, vcc, s[12:13]
	v_cmp_gt_i32_e64 s[12:13], v66, v136
	s_and_b64 s[10:11], s[10:11], s[12:13]
	v_cndmask_b32_e32 v66, v227, v50, vcc
	v_cmp_lt_i32_e32 vcc, v67, v100
	v_add_u32_e32 v50, 0xffffffa1, v81
	v_cmp_ge_i32_e64 s[12:13], v67, v136
	v_cndmask_b32_e64 v18, v227, v18, s[10:11]
	v_cmp_le_i32_e64 s[10:11], v50, v100
	s_and_b64 vcc, vcc, s[12:13]
	v_cmp_gt_i32_e64 s[12:13], v50, v136
	v_add_u32_e32 v50, 0xffffff82, v81
	s_and_b64 s[10:11], s[10:11], s[12:13]
	v_cndmask_b32_e32 v67, v227, v51, vcc
	v_cmp_le_i32_e32 vcc, v50, v100
	v_add_u32_e32 v51, 0xffffffa2, v81
	v_cmp_gt_i32_e64 s[12:13], v50, v136
	v_cndmask_b32_e64 v19, v227, v19, s[10:11]
	v_cmp_le_i32_e64 s[10:11], v51, v100
	s_and_b64 vcc, vcc, s[12:13]
	v_cmp_gt_i32_e64 s[12:13], v51, v136
	v_add_u32_e32 v50, 0xffffff83, v81
	s_and_b64 s[10:11], s[10:11], s[12:13]
	v_cndmask_b32_e32 v68, v227, v52, vcc
	v_cmp_le_i32_e32 vcc, v50, v100
	v_add_u32_e32 v51, 0xffffffa3, v81
	v_cmp_gt_i32_e64 s[12:13], v50, v136
	v_cndmask_b32_e64 v20, v227, v20, s[10:11]
	v_cmp_le_i32_e64 s[10:11], v51, v100
	s_and_b64 vcc, vcc, s[12:13]
	v_cmp_gt_i32_e64 s[12:13], v51, v136
	v_add_u32_e32 v50, 0xffffff88, v81
	s_and_b64 s[10:11], s[10:11], s[12:13]
	v_cndmask_b32_e32 v69, v227, v53, vcc
	v_cmp_le_i32_e32 vcc, v50, v100
	v_add_u32_e32 v51, 0xffffffa8, v81
	v_cmp_gt_i32_e64 s[12:13], v50, v136
	v_cndmask_b32_e64 v21, v227, v21, s[10:11]
	v_cmp_le_i32_e64 s[10:11], v51, v100
	s_and_b64 vcc, vcc, s[12:13]
	v_cmp_gt_i32_e64 s[12:13], v51, v136
	v_add_u32_e32 v50, 0xffffff89, v81
	s_and_b64 s[10:11], s[10:11], s[12:13]
	v_cndmask_b32_e32 v70, v227, v54, vcc
	v_cmp_le_i32_e32 vcc, v50, v100
	v_add_u32_e32 v51, 0xffffffa9, v81
	v_cmp_gt_i32_e64 s[12:13], v50, v136
	v_cndmask_b32_e64 v22, v227, v22, s[10:11]
	v_cmp_le_i32_e64 s[10:11], v51, v100
	s_and_b64 vcc, vcc, s[12:13]
	v_cmp_gt_i32_e64 s[12:13], v51, v136
	v_add_u32_e32 v50, 0xffffff8a, v81
	s_and_b64 s[10:11], s[10:11], s[12:13]
	v_cndmask_b32_e32 v71, v227, v55, vcc
	v_cmp_le_i32_e32 vcc, v50, v100
	v_add_u32_e32 v51, 0xffffffaa, v81
	v_cmp_gt_i32_e64 s[12:13], v50, v136
	v_cndmask_b32_e64 v23, v227, v23, s[10:11]
	v_cmp_le_i32_e64 s[10:11], v51, v100
	s_and_b64 vcc, vcc, s[12:13]
	v_cmp_gt_i32_e64 s[12:13], v51, v136
	v_add_u32_e32 v50, 0xffffff8b, v81
	s_and_b64 s[10:11], s[10:11], s[12:13]
	v_cndmask_b32_e32 v72, v227, v56, vcc
	v_cmp_le_i32_e32 vcc, v50, v100
	v_add_u32_e32 v51, 0xffffffab, v81
	v_cmp_gt_i32_e64 s[12:13], v50, v136
	v_cndmask_b32_e64 v24, v227, v24, s[10:11]
	v_cmp_le_i32_e64 s[10:11], v51, v100
	s_and_b64 vcc, vcc, s[12:13]
	v_cmp_gt_i32_e64 s[12:13], v51, v136
	v_add_u32_e32 v50, 0xffffff90, v81
	s_and_b64 s[10:11], s[10:11], s[12:13]
	v_cndmask_b32_e32 v73, v227, v57, vcc
	v_cmp_le_i32_e32 vcc, v50, v100
	v_add_u32_e32 v51, 0xffffffb0, v81
	v_cmp_gt_i32_e64 s[12:13], v50, v136
	v_cndmask_b32_e64 v25, v227, v25, s[10:11]
	v_cmp_le_i32_e64 s[10:11], v51, v100
	s_and_b64 vcc, vcc, s[12:13]
	v_cmp_gt_i32_e64 s[12:13], v51, v136
	v_add_u32_e32 v50, 0xffffff91, v81
	s_and_b64 s[10:11], s[10:11], s[12:13]
	v_cndmask_b32_e32 v74, v227, v58, vcc
	v_cmp_le_i32_e32 vcc, v50, v100
	v_add_u32_e32 v51, 0xffffffb1, v81
	v_cmp_gt_i32_e64 s[12:13], v50, v136
	v_cndmask_b32_e64 v26, v227, v26, s[10:11]
	v_cmp_le_i32_e64 s[10:11], v51, v100
	s_and_b64 vcc, vcc, s[12:13]
	v_cmp_gt_i32_e64 s[12:13], v51, v136
	v_add_u32_e32 v50, 0xffffff92, v81
	s_and_b64 s[10:11], s[10:11], s[12:13]
	v_cndmask_b32_e32 v75, v227, v59, vcc
	v_cmp_le_i32_e32 vcc, v50, v100
	v_add_u32_e32 v51, 0xffffffb2, v81
	v_cmp_gt_i32_e64 s[12:13], v50, v136
	v_cndmask_b32_e64 v27, v227, v27, s[10:11]
	v_cmp_le_i32_e64 s[10:11], v51, v100
	s_and_b64 vcc, vcc, s[12:13]
	v_cmp_gt_i32_e64 s[12:13], v51, v136
	v_add_u32_e32 v50, 0xffffff93, v81
	s_and_b64 s[10:11], s[10:11], s[12:13]
	v_cndmask_b32_e32 v76, v227, v60, vcc
	v_cmp_le_i32_e32 vcc, v50, v100
	v_add_u32_e32 v51, 0xffffffb3, v81
	v_cmp_gt_i32_e64 s[12:13], v50, v136
	v_cndmask_b32_e64 v28, v227, v28, s[10:11]
	v_cmp_le_i32_e64 s[10:11], v51, v100
	s_and_b64 vcc, vcc, s[12:13]
	v_cmp_gt_i32_e64 s[12:13], v51, v136
	v_add_u32_e32 v50, 0xffffff98, v81
	s_and_b64 s[10:11], s[10:11], s[12:13]
	v_cndmask_b32_e32 v77, v227, v61, vcc
	v_cmp_le_i32_e32 vcc, v50, v100
	v_add_u32_e32 v51, 0xffffffb8, v81
	v_cmp_gt_i32_e64 s[12:13], v50, v136
	v_cndmask_b32_e64 v29, v227, v29, s[10:11]
	v_cmp_le_i32_e64 s[10:11], v51, v100
	s_and_b64 vcc, vcc, s[12:13]
	v_cmp_gt_i32_e64 s[12:13], v51, v136
	v_add_u32_e32 v50, 0xffffff99, v81
	s_and_b64 s[10:11], s[10:11], s[12:13]
	v_cndmask_b32_e32 v78, v227, v62, vcc
	v_cmp_le_i32_e32 vcc, v50, v100
	v_add_u32_e32 v51, 0xffffffb9, v81
	v_cmp_gt_i32_e64 s[12:13], v50, v136
	v_cndmask_b32_e64 v30, v227, v30, s[10:11]
	v_cmp_le_i32_e64 s[10:11], v51, v100
	s_and_b64 vcc, vcc, s[12:13]
	v_cmp_gt_i32_e64 s[12:13], v51, v136
	v_add_u32_e32 v50, 0xffffff9a, v81
	s_and_b64 s[10:11], s[10:11], s[12:13]
	v_cndmask_b32_e32 v79, v227, v63, vcc
	v_cmp_le_i32_e32 vcc, v50, v100
	v_add_u32_e32 v51, 0xffffffba, v81
	v_cmp_gt_i32_e64 s[12:13], v50, v136
	v_cndmask_b32_e64 v31, v227, v31, s[10:11]
	v_cmp_le_i32_e64 s[10:11], v51, v100
	s_and_b64 vcc, vcc, s[12:13]
	v_cmp_gt_i32_e64 s[12:13], v51, v136
	v_add_u32_e32 v50, 0xffffff9b, v81
	s_and_b64 s[10:11], s[10:11], s[12:13]
	v_cndmask_b32_e32 v80, v227, v64, vcc
	v_cmp_le_i32_e32 vcc, v50, v100
	v_add_u32_e32 v51, 0xffffffbb, v81
	v_cmp_gt_i32_e64 s[12:13], v50, v136
	v_cndmask_b32_e64 v32, v227, v32, s[10:11]
	v_cmp_le_i32_e64 s[10:11], v51, v100
	s_and_b64 vcc, vcc, s[12:13]
	v_cmp_gt_i32_e64 s[12:13], v51, v136
	s_and_b64 s[10:11], s[10:11], s[12:13]
	v_cndmask_b32_e32 v81, v227, v65, vcc
	v_cndmask_b32_e64 v33, v227, v33, s[10:11]
	s_branch .LBB0_320

; __device__ __forceinline__ unsigned pk2(float lo, float hi) { f32x2 v = {lo, hi}; bf16x2_t b = __builtin_convertvector(v, bf16x2_t); return __builtin_bit_cast(unsigned, b); }
; template <int DQ, int DK1, int DV, int MODE> ...
;     ...
;     float l; { auto rr = __builtin_amdgcn_permlane32_swap(__float_as_uint(l_run), __float_as_uint(l_run), false, false); l = __uint_as_float(rr[0]) + __uint_as_float(rr[1]); }
;     if (MODE == 2) l += __builtin_amdgcn_exp2f(sink2 - m_run);
;     const float inv = 1.0f / l;
;     bf16_t* orow = Op + (tok0 + qpos) * (size_t)DM;
; #pragma unroll
;     for (int d = 0; d < DV / 32; ++d)
; #pragma unroll
;         for (int g = 0; g < 4; ++g) { u32x2 w; w[0] = pk2(o[d][4 * g] * inv, o[d][4 * g + 1] * inv); w[1] = pk2(o[d][4 * g + 2] * inv, o[d][4 * g + 3] * inv);
;             *(u32x2*)(orow + 32 * d + 8 * g + 4 * hi) = w; }
.Lswa_epi:
	s_mov_b32 s2, 0x3fb8aa3b
	v_fma_f32 v1, v1, s2, -v139
	v_exp_f32_e32 v1, v1
	v_mov_b32_e32 v18, v138
	s_nop 1
	v_permlane32_swap_b32_e32 v138, v18
	v_add_f32_e32 v18, v138, v18
	v_add_f32_e32 v1, v1, v18
	v_div_scale_f32 v18, s[2:3], v1, v1, 1.0
	v_rcp_f32_e32 v19, v18
	v_readlane_b32 s2, v254, 38
	s_add_u32 s2, s2, s20
	v_readlane_b32 s3, v254, 39
	v_fma_f32 v20, -v18, v19, 1.0
	v_fmac_f32_e32 v19, v20, v19
	v_div_scale_f32 v20, vcc, 1.0, v1, 1.0
	v_mul_f32_e32 v21, v20, v19
	v_fma_f32 v22, -v18, v21, v20
	v_fmac_f32_e32 v21, v22, v19
	v_fma_f32 v18, -v18, v21, v20
	v_div_fmas_f32 v18, v18, v19, v21
	s_addc_u32 s3, s3, 0
	v_div_fixup_f32 v18, v18, v1, 1.0
	v_lshlrev_b64 v[20:21], 12, v[98:99]
	v_lshl_add_u64 v[20:21], s[2:3], 0, v[20:21]
	v_lshlrev_b32_e32 v22, 1, v111
	v_mov_b32_e32 v23, v0
	v_pk_mul_f32 v[2:3], v[2:3], v[18:19] op_sel_hi:[1,0]
	v_pk_mul_f32 v[4:5], v[4:5], v[18:19] op_sel_hi:[1,0]
	v_lshl_add_u64 v[20:21], v[20:21], 0, v[22:23]
	v_cvt_pk_bf16_f32 v2, v2, v3
	v_cvt_pk_bf16_f32 v3, v4, v5
	global_store_dwordx2 v[20:21], v[2:3], off
	v_pk_mul_f32 v[2:3], v[6:7], v[18:19] op_sel_hi:[1,0]
	v_pk_mul_f32 v[4:5], v[8:9], v[18:19] op_sel_hi:[1,0]
	v_cvt_pk_bf16_f32 v2, v2, v3
	v_cvt_pk_bf16_f32 v3, v4, v5
	global_store_dwordx2 v[20:21], v[2:3], off offset:16
	v_pk_mul_f32 v[2:3], v[10:11], v[18:19] op_sel_hi:[1,0]
	v_pk_mul_f32 v[4:5], v[12:13], v[18:19] op_sel_hi:[1,0]
	v_cvt_pk_bf16_f32 v2, v2, v3
	v_cvt_pk_bf16_f32 v3, v4, v5
	global_store_dwordx2 v[20:21], v[2:3], off offset:32
	v_pk_mul_f32 v[2:3], v[14:15], v[18:19] op_sel_hi:[1,0]
	v_pk_mul_f32 v[4:5], v[16:17], v[18:19] op_sel_hi:[1,0]
	v_cvt_pk_bf16_f32 v2, v2, v3
	v_cvt_pk_bf16_f32 v3, v4, v5
	global_store_dwordx2 v[20:21], v[2:3], off offset:48
	v_pk_mul_f32 v[2:3], v[34:35], v[18:19] op_sel_hi:[1,0]
	v_pk_mul_f32 v[4:5], v[36:37], v[18:19] op_sel_hi:[1,0]
	v_cvt_pk_bf16_f32 v2, v2, v3
	v_cvt_pk_bf16_f32 v3, v4, v5
	global_store_dwordx2 v[20:21], v[2:3], off offset:64
	v_pk_mul_f32 v[2:3], v[38:39], v[18:19] op_sel_hi:[1,0]
	v_pk_mul_f32 v[4:5], v[40:41], v[18:19] op_sel_hi:[1,0]
	v_cvt_pk_bf16_f32 v2, v2, v3
	v_cvt_pk_bf16_f32 v3, v4, v5
	global_store_dwordx2 v[20:21], v[2:3], off offset:80
	v_pk_mul_f32 v[2:3], v[42:43], v[18:19] op_sel_hi:[1,0]
	v_pk_mul_f32 v[4:5], v[44:45], v[18:19] op_sel_hi:[1,0]
	v_cvt_pk_bf16_f32 v2, v2, v3
	v_cvt_pk_bf16_f32 v3, v4, v5
	global_store_dwordx2 v[20:21], v[2:3], off offset:96
	v_pk_mul_f32 v[2:3], v[46:47], v[18:19] op_sel_hi:[1,0]
	v_pk_mul_f32 v[4:5], v[48:49], v[18:19] op_sel_hi:[1,0]
	v_cvt_pk_bf16_f32 v2, v2, v3
	v_cvt_pk_bf16_f32 v3, v4, v5
	global_store_dwordx2 v[20:21], v[2:3], off offset:112
	s_mov_b64 s[2:3], 0
